# v044 + MLA tile-loop head: wave-uniform flag test (s_mov_b64/s_andn2/vccnz) replaced by a direct scc branch to the counted wait
# baseline (speedup 1.0000x reference)
.LBB0_1575:
	s_lshl_b32 s2, s47, 4
	s_ashr_i32 s20, s47, 8
	s_and_b32 s2, s2, 0xffffff00
	s_add_i32 s16, s2, 0x2000
	s_lshl_b32 s2, s20, 12
	s_and_b32 s6, s47, 15
	s_ashr_i32 s21, s20, 31
	s_ashr_i32 s3, s2, 31
	s_add_u32 s2, s2, 0x2400
	s_addc_u32 s3, s3, 0
	s_ashr_i32 s17, s16, 31
	s_mul_i32 s19, s16, 0x1800
	s_mul_hi_i32 s18, s16, 0x1800
	s_add_u32 s19, s28, s19
	s_addc_u32 s18, s29, s18
	s_mul_i32 s22, s6, 0x180
	s_add_u32 s22, s19, s22
	s_addc_u32 s23, s18, 0
	s_lshl_b64 s[18:19], s[20:21], 20
	s_lshl_b64 s[24:25], s[20:21], 21
	s_add_u32 s26, s30, s24
	s_addc_u32 s27, s31, s25
	s_lshl_b32 s50, s6, 7
	s_lshl_b32 s6, s6, 8
	s_add_u32 s26, s26, s6
	s_addc_u32 s27, s27, 0
	s_add_u32 s24, s34, s24
	v_lshlrev_b32_e32 v130, 1, v140
	v_add_u32_e32 v20, 0xc000, v167
	s_addc_u32 s25, s35, s25
	v_lshl_add_u64 v[2:3], s[22:23], 0, v[130:131]
	v_mov_b32_e32 v139, v131
	v_readfirstlane_b32 s22, v20
	v_add_u32_e32 v22, 0xe000, v167
	s_add_u32 s24, s24, s6
	v_lshl_add_u64 v[14:15], v[2:3], 0, v[138:139]
	v_lshl_add_u64 v[18:19], s[26:27], 0, v[132:133]
	s_mov_b32 m0, s22
	v_readfirstlane_b32 s22, v22
	s_addc_u32 s25, s25, 0
	s_lshl_b64 s[20:21], s[20:21], 16
	global_load_dwordx4 v[98:101], v[14:15], off
	global_load_dwordx4 v[102:105], v[14:15], off offset:32
	global_load_dwordx4 v[106:109], v[14:15], off offset:64
	global_load_dwordx4 v[110:113], v[14:15], off offset:96
	global_load_dwordx4 v[114:117], v[14:15], off offset:128
	global_load_dwordx4 v[118:121], v[14:15], off offset:160
	global_load_dwordx4 v[122:125], v[14:15], off offset:192
	global_load_dwordx4 v[126:129], v[14:15], off offset:224
	global_load_dwordx4 v[2:5], v[14:15], off offset:256
	global_load_dwordx4 v[6:9], v[14:15], off offset:288
	global_load_dwordx4 v[10:13], v[14:15], off offset:320
	s_nop 0
	global_load_dwordx4 v[14:17], v[14:15], off offset:352
	v_lshl_add_u64 v[20:21], v[18:19], 0, s[8:9]
	global_load_lds_dwordx4 v[18:19], off
	s_mov_b32 m0, s22
	v_readfirstlane_b32 s22, v167
	v_add_u32_e32 v24, 0x2000, v167
	s_add_u32 s54, s36, s20
	global_load_lds_dwordx4 v[20:21], off
	v_lshl_add_u64 v[20:21], s[24:25], 0, v[134:135]
	s_mov_b32 m0, s22
	v_readfirstlane_b32 s22, v24
	s_addc_u32 s55, s37, s21
	global_load_lds_dwordx4 v[20:21], off
	v_lshl_add_u64 v[22:23], v[20:21], 0, s[8:9]
	s_mov_b32 m0, s22
	v_readfirstlane_b32 s22, v168
	v_add_u32_e32 v179, s42, v182
	global_load_lds_dwordx4 v[22:23], off
	v_lshl_add_u64 v[22:23], s[54:55], 0, v[136:137]
	s_mov_b32 m0, s22
	v_readfirstlane_b32 s22, v179
	global_load_lds_dwordx4 v[22:23], off
	v_lshl_add_u64 v[24:25], v[18:19], 0, s[10:11]
	s_mov_b32 m0, s22
	v_add_u32_e32 v180, s43, v182
	global_load_lds_dwordx4 v[24:25], off
	v_readfirstlane_b32 s22, v180
	v_add_u32_e32 v24, 0x4000, v167
	v_lshl_add_u64 v[18:19], v[18:19], 0, s[12:13]
	s_mov_b32 m0, s22
	v_readfirstlane_b32 s22, v24
	global_load_lds_dwordx4 v[18:19], off
	v_lshl_add_u64 v[18:19], v[20:21], 0, s[10:11]
	s_mov_b32 m0, s22
	v_add_u32_e32 v181, s44, v182
	global_load_lds_dwordx4 v[18:19], off
	v_lshl_add_u64 v[18:19], v[20:21], 0, s[12:13]
	v_add_u32_e32 v20, 0x6000, v167
	s_lshl_b64 s[24:25], s[2:3], 7
	v_readfirstlane_b32 s22, v20
	s_mov_b32 m0, s22
	v_readfirstlane_b32 s22, v181
	global_load_lds_dwordx4 v[18:19], off
	v_lshl_add_u64 v[18:19], v[22:23], 0, s[14:15]
	s_mov_b32 m0, s22
	s_lshl_b64 s[22:23], s[2:3], 11
	global_load_lds_dwordx4 v[18:19], off
	s_add_u32 s51, s34, s6
	s_waitcnt vmcnt(0)
	ds_write_b128 v175, v[2:5]
	ds_write_b128 v176, v[6:9]
	ds_write_b128 v177, v[10:13]
	ds_write_b128 v178, v[14:17]
	s_addc_u32 s54, s35, 0
	v_mov_b32_e32 v16, v131
	v_mov_b32_e32 v17, v131
	s_add_u32 s55, s30, s6
	v_mov_b32_e32 v2, v131
	v_mov_b32_e32 v3, v131
	v_mov_b32_e32 v4, v131
	v_mov_b32_e32 v5, v131
	v_mov_b32_e32 v6, v131
	v_mov_b32_e32 v7, v131
	v_mov_b32_e32 v8, v131
	v_mov_b32_e32 v9, v131
	v_mov_b32_e32 v10, v131
	v_mov_b32_e32 v11, v131
	v_mov_b32_e32 v12, v131
	v_mov_b32_e32 v13, v131
	v_mov_b32_e32 v14, v131
	v_mov_b32_e32 v15, v131
	v_mov_b64_e32 v[64:65], v[16:17]
	v_mov_b64_e32 v[48:49], v[16:17]
	v_mov_b64_e32 v[32:33], v[16:17]
	s_addc_u32 s56, s31, 0
	v_mov_b64_e32 v[62:63], v[14:15]
	v_mov_b64_e32 v[60:61], v[12:13]
	v_mov_b64_e32 v[58:59], v[10:11]
	v_mov_b64_e32 v[56:57], v[8:9]
	v_mov_b64_e32 v[54:55], v[6:7]
	v_mov_b64_e32 v[52:53], v[4:5]
	v_mov_b64_e32 v[50:51], v[2:3]
	v_mov_b64_e32 v[46:47], v[14:15]
	v_mov_b64_e32 v[44:45], v[12:13]
	v_mov_b64_e32 v[42:43], v[10:11]
	v_mov_b64_e32 v[40:41], v[8:9]
	v_mov_b64_e32 v[38:39], v[6:7]
	v_mov_b64_e32 v[36:37], v[4:5]
	v_mov_b64_e32 v[34:35], v[2:3]
	v_mov_b64_e32 v[30:31], v[14:15]
	v_mov_b64_e32 v[28:29], v[12:13]
	v_mov_b64_e32 v[26:27], v[10:11]
	v_mov_b64_e32 v[24:25], v[8:9]
	v_mov_b64_e32 v[22:23], v[6:7]
	v_mov_b64_e32 v[20:21], v[4:5]
	v_mov_b64_e32 v[18:19], v[2:3]
	s_mov_b32 s57, s7
	s_mov_b32 s58, s7
	v_mov_b32_e32 v139, 0xf149f2ca
	v_mov_b32_e32 v184, 0
	s_cmpk_gt_u32 s58, 0x46
	s_cbranch_scc0 .LBB0_1578
	s_branch .LBB0_1577
.LBB0_1577:
	s_waitcnt vmcnt(0)
	s_branch .LBB0_1580
.LBB0_1578:
	s_waitcnt vmcnt(5)
	s_branch .LBB0_1580
.LBB0_1576:
	v_mov_b32_e32 v184, v66
	s_cmpk_gt_u32 s58, 0x46
	s_cbranch_scc1 .LBB0_1577
	s_waitcnt vmcnt(5)
